# r1: next tile's conv inputs land in AGPRs and are picked up at the next tile's top; no vmcnt(0) before the tile's first barrier
# baseline (speedup 1.0000x reference)
.LBB0_384:
	s_mov_b64 s[64:65], -1
	s_mov_b64 s[66:67], 0
	s_cmp_lt_i32 s90, 4
	s_cselect_b64 s[0:1], -1, 0
	s_cmp_gt_i32 s91, 3
	s_cselect_b64 s[4:5], -1, 0
	s_and_b64 s[0:1], s[0:1], s[4:5]
	s_andn2_b64 vcc, exec, s[0:1]
	s_cbranch_vccnz .LBB0_589
	s_waitcnt lgkmcnt(0)
	s_load_dword s3, s[96:97], 0x128
	s_add_u32 s6, s96, 0x128
	s_addc_u32 s7, s97, 0
	s_cmpk_gt_i32 s2, 0x9ff
	s_cbranch_scc1 .LBB0_535
	v_readlane_b32 s8, v126, 2
	v_readlane_b32 s14, v126, 8
	v_readlane_b32 s15, v126, 9
	v_readlane_b32 s12, v126, 6
	v_readlane_b32 s13, v126, 7
	s_mov_b64 s[26:27], s[14:15]
	v_readlane_b32 s9, v126, 3
	s_add_u32 s8, s26, 0x233e8000
	v_readlane_b32 s10, v126, 4
	s_addc_u32 s9, s27, 0
	v_readlane_b32 s11, v126, 5
	s_add_u32 s10, s26, 0x18c40000
	s_addc_u32 s11, s27, 0
	s_mov_b64 s[24:25], s[12:13]
	s_add_u32 s12, s26, 0x18ebc000
	s_addc_u32 s13, s27, 0
	s_add_u32 s14, s26, 0x213e8000
	s_addc_u32 s15, s27, 0
	s_add_u32 s16, s26, 0x223e8000
	s_addc_u32 s17, s27, 0
	s_add_u32 s18, s26, 0x18ec8000
	s_addc_u32 s19, s27, 0
	s_add_u32 s20, s26, 0x22be8000
	s_addc_u32 s21, s27, 0
	s_add_u32 s22, s26, 0x18f48000
	s_addc_u32 s23, s27, 0
	s_add_u32 s24, s26, 0x253e8000
	v_mbcnt_lo_u32_b32 v0, -1, 0
	s_addc_u32 s25, s27, 0
	v_mov_b32_e32 v73, 0
	s_mov_b64 s[26:27], 0
	s_movk_i32 s36, 0x100
	s_movk_i32 s37, 0x1000
	s_movk_i32 s38, 0x104
	s_movk_i32 s39, 0x90
	s_waitcnt vmcnt(4)
	v_mov_b32_e32 v113, 0x3c088889
	s_add_i32 s40, 0, 0xd500
	s_add_i32 s41, 0, 0x6500
	s_movk_i32 s42, 0x110
	s_movk_i32 s43, 0xfeff
	s_mov_b32 s44, 0xff61b1e6
	v_mbcnt_hi_u32_b32 v80, -1, v0
	v_mov_b32_e32 v81, 0xf149f2ca
	s_mov_b32 s45, s2
	s_waitcnt vmcnt(3)
	v_mov_b32_e32 v115, 0
	s_waitcnt vmcnt(1)
	v_mov_b32_e32 v124, 0
	v_mov_b32_e32 v125, 0
	v_accvgpr_write_b32 a40, 0
	v_accvgpr_write_b32 a41, 0
	v_accvgpr_write_b32 a42, 0
	s_branch .LBB0_389

.LBB0_416:
	s_waitcnt vmcnt(32)
	s_mov_b64 exec, s[66:67]
	v_accvgpr_read_b32 v39, a8
	v_accvgpr_read_b32 v84, a9
	v_accvgpr_read_b32 v85, a10
	v_accvgpr_read_b32 v86, a11
	v_accvgpr_read_b32 v105, a12
	v_accvgpr_read_b32 v106, a13
	v_accvgpr_read_b32 v107, a14
	v_accvgpr_read_b32 v108, a15
	v_accvgpr_read_b32 v109, a16
	v_accvgpr_read_b32 v110, a17
	v_accvgpr_read_b32 v83, a18
	v_or_b32_e32 v88, v84, v39
	v_or_b32_e32 v87, v86, v85
	v_or_b32_e32 v86, v106, v105
	v_or_b32_e32 v85, v108, v107
	v_or_b32_e32 v84, v110, v109
	s_mov_b64 exec, -1
	v_mov_b32_e32 v89, v77
	v_mov_b32_e32 v1, v73
	v_and_b32_e32 v82, 63, v89
	v_or_b32_e32 v0, v82, v74
	v_lshlrev_b64 v[0:1], 2, v[0:1]
	v_readlane_b32 s80, v126, 31
	v_lshl_add_u64 v[2:3], s[62:63], 0, v[0:1]
	v_readlane_b32 s81, v126, 32
	v_add_co_u32_e32 v4, vcc, s37, v2
	s_nop 0
	v_lshl_add_u64 v[0:1], s[80:81], 0, v[0:1]
	v_addc_co_u32_e32 v5, vcc, 0, v3, vcc
	s_mov_b64 exec, s[64:65]
	global_load_dword a43, v[0:1], off
	global_load_dword a44, v[2:3], off
	global_load_dword a45, v[2:3], off offset:2048
	global_load_dword a46, v[4:5], off
	global_load_dword a47, v[4:5], off offset:2048
	s_mov_b64 exec, -1
	v_ashrrev_i32_e32 v90, 6, v89
	v_and_b32_e32 v103, 1, v90
	v_and_b32_e32 v97, 15, v89
	v_lshlrev_b32_e32 v6, 10, v103
	v_or3_b32 v2, v6, v74, v97
	v_and_b32_e32 v72, 48, v89
	v_lshlrev_b32_e32 v3, 9, v103
	v_lshl_add_u64 v[0:1], s[10:11], 0, v[72:73]
	v_or3_b32 v4, v3, v74, v97
	v_lshlrev_b32_e32 v2, 7, v2
	v_mov_b32_e32 v3, v73
	v_lshl_add_u64 v[0:1], v[0:1], 0, v[2:3]
	s_mov_b32 s0, 0x10000
	v_add_co_u32_e32 v2, vcc, s0, v0
	s_mov_b32 s0, 0x11000
	s_nop 0
	v_addc_co_u32_e32 v3, vcc, 0, v1, vcc
	v_add_co_u32_e32 v6, vcc, s0, v0
	v_mov_b32_e32 v5, v73
	s_nop 0
	v_addc_co_u32_e32 v7, vcc, 0, v1, vcc
	v_add_co_u32_e32 v12, vcc, s37, v0
	v_readlane_b32 s84, v126, 35
	v_readlane_b32 s85, v126, 36
	v_readlane_b32 s88, v126, 39
	v_readlane_b32 s89, v126, 40
	s_mov_b64 exec, s[64:65]
	global_load_dwordx4 a[52:55], v[0:1], off
	global_load_dwordx4 a[56:59], v[0:1], off offset:64
	s_mov_b64 exec, -1
	v_lshlrev_b64 v[8:9], 2, v[4:5]
	s_mov_b64 exec, s[64:65]
	global_load_dwordx4 a[60:63], v[2:3], off offset:64
	global_load_dwordx4 a[64:67], v[2:3], off offset:2048
	global_load_dwordx4 a[68:71], v[0:1], off offset:2048
	global_load_dwordx4 a[72:75], v[0:1], off offset:2112
	global_load_dwordx4 a[76:79], v[2:3], off offset:2112
	s_mov_b64 exec, -1
	v_or_b32_e32 v2, 16, v4
	v_mov_b32_e32 v3, v73
	v_addc_co_u32_e32 v13, vcc, 0, v1, vcc
	v_or_b32_e32 v0, 32, v4
	v_mov_b32_e32 v1, v73
	v_or_b32_e32 v4, 48, v4
	v_lshl_add_u64 v[32:33], s[84:85], 0, v[8:9]
	v_lshl_add_u64 v[34:35], s[88:89], 0, v[8:9]
	v_lshl_add_u64 v[8:9], s[12:13], 0, v[8:9]
	v_lshl_add_u64 v[2:3], v[2:3], 2, s[12:13]
	v_lshl_add_u64 v[14:15], v[0:1], 2, s[12:13]
	v_lshl_add_u64 v[4:5], v[4:5], 2, s[12:13]
	s_mov_b64 exec, s[64:65]
	global_load_dword a48, v[8:9], off
	global_load_dword a49, v[2:3], off
	global_load_dwordx4 a[80:83], v[12:13], off
	global_load_dwordx4 a[84:87], v[6:7], off offset:-4096
	global_load_dwordx4 a[88:91], v[6:7], off
	global_load_dwordx4 a[92:95], v[12:13], off offset:64
	s_mov_b64 exec, -1
	s_nop 0
	s_mov_b64 exec, s[64:65]
	global_load_dwordx4 a[96:99], v[12:13], off offset:2048
	global_load_dwordx4 a[100:103], v[6:7], off offset:64
	global_load_dwordx4 a[104:107], v[6:7], off offset:2048
	global_load_dword a50, v[14:15], off
	global_load_dword a51, v[4:5], off
	s_mov_b64 exec, -1
	s_nop 0
	s_mov_b64 exec, s[64:65]
	global_load_dwordx4 a[108:111], v[12:13], off offset:2112
	s_mov_b64 exec, -1
	s_nop 0
	s_mov_b64 exec, s[64:65]
	global_load_dwordx4 a[112:115], v[6:7], off offset:2112
	s_mov_b64 exec, -1
	s_nop 0
	s_mov_b64 exec, s[64:65]
	global_load_dword a116, v[32:33], off
	global_load_dword a117, v[32:33], off offset:64
	global_load_dword a118, v[32:33], off offset:128
	global_load_dword a119, v[32:33], off offset:192
	global_load_dword a120, v[34:35], off
	global_load_dword a121, v[34:35], off offset:64
	global_load_dword a122, v[34:35], off offset:128
	global_load_dword a123, v[34:35], off offset:192
	s_mov_b64 exec, -1
	v_lshlrev_b32_e32 v33, 16, v88
	v_and_b32_e32 v35, 0xffff0000, v88
	v_lshlrev_b32_e32 v79, 16, v87
	v_and_b32_e32 v105, 0xffff0000, v87
	v_lshl_add_u32 v32, v82, 2, 0
	s_movk_i32 s0, 0x820
	v_lshlrev_b32_e32 v34, 1, v82
	v_sub_u32_e32 v34, v32, v34
	v_lshlrev_b32_e32 v106, 16, v86
	v_and_b32_e32 v107, 0xffff0000, v86
	v_lshlrev_b32_e32 v108, 16, v85
	v_and_b32_e32 v109, 0xffff0000, v85
	v_lshlrev_b32_e32 v110, 16, v84
	v_and_b32_e32 v111, 0xffff0000, v84
	v_lshlrev_b32_e32 v112, 16, v83
	s_waitcnt lgkmcnt(0)
	s_cmp_eq_u64 s[64:65], 0
	s_cbranch_scc1 .Lr1w_have
	s_waitcnt vmcnt(0)
.Lr1w_have:
	v_accvgpr_read_b32 v38, a43
	v_accvgpr_read_b32 v39, a44
	v_accvgpr_read_b32 v75, a45
	v_accvgpr_read_b32 v76, a46
	v_accvgpr_read_b32 v78, a47
	v_accvgpr_read_b32 v64, a52
	v_accvgpr_read_b32 v65, a53
	v_accvgpr_read_b32 v66, a54
	v_accvgpr_read_b32 v67, a55
	v_accvgpr_read_b32 v60, a56
	v_accvgpr_read_b32 v61, a57
	v_accvgpr_read_b32 v62, a58
	v_accvgpr_read_b32 v63, a59
	v_accvgpr_read_b32 v56, a60
	v_accvgpr_read_b32 v57, a61
	v_accvgpr_read_b32 v58, a62
	v_accvgpr_read_b32 v59, a63
	v_accvgpr_read_b32 v44, a64
	v_accvgpr_read_b32 v45, a65
	v_accvgpr_read_b32 v46, a66
	v_accvgpr_read_b32 v47, a67
	v_accvgpr_read_b32 v52, a68
	v_accvgpr_read_b32 v53, a69
	v_accvgpr_read_b32 v54, a70
	v_accvgpr_read_b32 v55, a71
	v_accvgpr_read_b32 v48, a72
	v_accvgpr_read_b32 v49, a73
	v_accvgpr_read_b32 v50, a74
	v_accvgpr_read_b32 v51, a75
	v_accvgpr_read_b32 v40, a76
	v_accvgpr_read_b32 v41, a77
	v_accvgpr_read_b32 v42, a78
	v_accvgpr_read_b32 v43, a79
	v_accvgpr_read_b32 v102, a48
	v_accvgpr_read_b32 v99, a49
	v_accvgpr_read_b32 v24, a80
	v_accvgpr_read_b32 v25, a81
	v_accvgpr_read_b32 v26, a82
	v_accvgpr_read_b32 v27, a83
	v_accvgpr_read_b32 v68, a84
	v_accvgpr_read_b32 v69, a85
	v_accvgpr_read_b32 v70, a86
	v_accvgpr_read_b32 v71, a87
	v_accvgpr_read_b32 v16, a88
	v_accvgpr_read_b32 v17, a89
	v_accvgpr_read_b32 v18, a90
	v_accvgpr_read_b32 v19, a91
	v_accvgpr_read_b32 v28, a92
	v_accvgpr_read_b32 v29, a93
	v_accvgpr_read_b32 v30, a94
	v_accvgpr_read_b32 v31, a95
	v_accvgpr_read_b32 v8, a96
	v_accvgpr_read_b32 v9, a97
	v_accvgpr_read_b32 v10, a98
	v_accvgpr_read_b32 v11, a99
	v_accvgpr_read_b32 v20, a100
	v_accvgpr_read_b32 v21, a101
	v_accvgpr_read_b32 v22, a102
	v_accvgpr_read_b32 v23, a103
	v_accvgpr_read_b32 v0, a104
	v_accvgpr_read_b32 v1, a105
	v_accvgpr_read_b32 v2, a106
	v_accvgpr_read_b32 v3, a107
	v_accvgpr_read_b32 v95, a50
	v_accvgpr_read_b32 v92, a51
	v_accvgpr_read_b32 v12, a108
	v_accvgpr_read_b32 v13, a109
	v_accvgpr_read_b32 v14, a110
	v_accvgpr_read_b32 v15, a111
	v_accvgpr_read_b32 v4, a112
	v_accvgpr_read_b32 v5, a113
	v_accvgpr_read_b32 v6, a114
	v_accvgpr_read_b32 v7, a115
	v_accvgpr_read_b32 v104, a116
	v_accvgpr_read_b32 v100, a117
	v_accvgpr_read_b32 v96, a118
	v_accvgpr_read_b32 v93, a119
	v_accvgpr_read_b32 v101, a120
	v_accvgpr_read_b32 v98, a121
	v_accvgpr_read_b32 v94, a122
	v_accvgpr_read_b32 v91, a123
	s_mov_b64 s[64:65], 0
	s_mov_b64 s[66:67], -1
	s_add_i32 s4, s34, s3
	s_cmpk_lt_i32 s4, 0x800
	v_readlane_b32 s82, v126, 33
	v_readlane_b32 s83, v126, 34
	v_readlane_b32 s86, v126, 37
	v_readlane_b32 s87, v126, 38
	v_readlane_b32 s90, v126, 41
	v_readlane_b32 s91, v126, 42
	v_readlane_b32 s92, v126, 43
	v_readlane_b32 s93, v126, 44
	v_readlane_b32 s94, v126, 45
	v_readlane_b32 s95, v126, 46
	s_waitcnt vmcnt(31)
	v_fma_f32 v33, v39, v33, v38
	s_waitcnt vmcnt(30)
	v_fmac_f32_e32 v33, v75, v35
	s_waitcnt vmcnt(29)
	v_fmac_f32_e32 v33, v76, v79
	s_waitcnt vmcnt(28)
	v_fmac_f32_e32 v33, v78, v105
	v_mad_u64_u32 v[36:37], s[0:1], v90, s0, v[32:33]
	s_movk_i32 s0, 0x480
	ds_write_b32 v36, v33
	v_mad_u64_u32 v[36:37], s[0:1], v90, s0, v[34:35]
	v_fma_f32 v35, v39, v35, v38
	v_fmac_f32_e32 v35, v75, v79
	v_cvt_pk_bf16_f32 v33, v33, v73
	ds_write_b16 v36, v33 offset:16640
	v_fmac_f32_e32 v35, v76, v105
	v_lshl_or_b32 v36, v90, 3, 1
	v_fmac_f32_e32 v35, v78, v106
	v_mad_u64_u32 v[32:33], s[0:1], v36, s38, v[32:33]
	ds_write_b32 v32, v35
	v_cvt_pk_bf16_f32 v33, v35, v73
	v_mad_u64_u32 v[34:35], s[0:1], v36, s39, v[34:35]
	ds_write_b16 v34, v33 offset:16640
	v_fma_f32 v33, v39, v79, v38
	v_fmac_f32_e32 v33, v75, v105
	v_fmac_f32_e32 v33, v76, v106
	v_fmac_f32_e32 v33, v78, v107
	ds_write_b32 v32, v33 offset:260
	v_cvt_pk_bf16_f32 v33, v33, v73
	ds_write_b16 v34, v33 offset:16784
	v_fma_f32 v33, v39, v105, v38
	v_fmac_f32_e32 v33, v75, v106
	v_fmac_f32_e32 v33, v76, v107
	v_fmac_f32_e32 v33, v78, v108
	ds_write_b32 v32, v33 offset:520
	v_cvt_pk_bf16_f32 v33, v33, v73
	ds_write_b16 v34, v33 offset:16928
	v_fma_f32 v33, v39, v106, v38
	v_fmac_f32_e32 v33, v75, v107
	v_fmac_f32_e32 v33, v76, v108
	v_fmac_f32_e32 v33, v78, v109
	ds_write_b32 v32, v33 offset:780
	v_cvt_pk_bf16_f32 v33, v33, v73
	ds_write_b16 v34, v33 offset:17072
	v_fma_f32 v33, v39, v107, v38
	v_fmac_f32_e32 v33, v75, v108
	v_fmac_f32_e32 v33, v76, v109
	v_fmac_f32_e32 v33, v78, v110
	ds_write_b32 v32, v33 offset:1040
	v_cvt_pk_bf16_f32 v33, v33, v73
	ds_write_b16 v34, v33 offset:17216
	v_fma_f32 v33, v39, v108, v38
	v_fmac_f32_e32 v38, v39, v109
	v_fmac_f32_e32 v33, v75, v109
	v_fmac_f32_e32 v38, v75, v110
	v_fmac_f32_e32 v33, v76, v110
	v_fmac_f32_e32 v38, v76, v111
	v_fmac_f32_e32 v33, v78, v111
	v_fmac_f32_e32 v38, v78, v112
	ds_write_b32 v32, v33 offset:1300
	v_cvt_pk_bf16_f32 v33, v33, v73
	ds_write_b16 v34, v33 offset:17360
	ds_write_b32 v32, v38 offset:1560
	v_cvt_pk_bf16_f32 v32, v38, v73
	s_mov_b64 s[0:1], -1
	v_ashrrev_i32_e32 v38, 3, v89
	ds_write_b16 v34, v32 offset:17504
	s_cbranch_scc1 .LBB0_418
	v_ashrrev_i32_e32 v32, 3, v89
	s_mov_b64 s[0:1], 0
.LBB0_418:
	s_andn2_b64 vcc, exec, s[0:1]
	s_mov_b64 s[90:91], s[30:31]
	s_cbranch_vccnz .LBB0_442
	s_lshl_b32 s0, s4, 3
	s_and_b32 s1, s0, 0xffffffc0
	s_cmpk_lt_i32 s1, 0x2000
	s_movk_i32 s30, 0xff00
	s_cselect_b32 s30, s30, 0xfffff800
	s_cselect_b32 s5, s36, 0x800
	s_and_b32 s30, s30, s0
	s_lshl_b32 s0, s4, 6
	v_and_b32_e32 v33, -8, v38
	s_and_b32 s0, s0, 0x1c0
	v_add_u32_e32 v34, s1, v33
	v_or_b32_e32 v32, s0, v82
	v_add_u32_e32 v36, -2, v34
	s_add_i32 s31, s30, s5
	v_lshlrev_b32_e32 v32, 1, v32
	v_mov_b32_e32 v33, v73
	v_cmp_le_i32_e32 vcc, s30, v36
	v_cmp_gt_i32_e64 s[4:5], s31, v36
	v_lshl_add_u64 v[32:33], s[8:9], 0, v[32:33]
	s_and_b64 s[4:5], vcc, s[4:5]
	v_accvgpr_write_b32 a9, 0
	v_accvgpr_write_b32 a8, 0
	s_and_saveexec_b64 s[0:1], s[4:5]
	s_cbranch_execz .LBB0_421
	v_ashrrev_i32_e32 v37, 31, v36
	v_lshlrev_b64 v[86:87], 10, v[36:37]
	v_lshl_add_u64 v[86:87], v[32:33], 0, v[86:87]
	global_load_ushort a8, v[86:87], off
.LBB0_421:
	s_or_b64 exec, exec, s[0:1]
	v_or_b32_e32 v36, 1, v36
	v_cmp_le_i32_e32 vcc, s30, v36
	v_cmp_gt_i32_e64 s[4:5], s31, v36
	s_and_b64 s[4:5], vcc, s[4:5]
	s_and_saveexec_b64 s[0:1], s[4:5]
	s_cbranch_execz .LBB0_423
	v_ashrrev_i32_e32 v37, 31, v36
	v_lshlrev_b64 v[36:37], 10, v[36:37]
	v_lshl_add_u64 v[36:37], v[32:33], 0, v[36:37]
	global_load_short_d16_hi a9, v[36:37], off
.LBB0_423:
	s_or_b64 exec, exec, s[0:1]
	v_cmp_le_i32_e32 vcc, s30, v34
	v_cmp_gt_i32_e64 s[4:5], s31, v34
	s_and_b64 s[4:5], vcc, s[4:5]
	v_accvgpr_write_b32 a11, 0
	v_accvgpr_write_b32 a10, 0
	s_and_saveexec_b64 s[0:1], s[4:5]
	s_cbranch_execz .LBB0_425
	v_ashrrev_i32_e32 v35, 31, v34
	v_lshlrev_b64 v[36:37], 10, v[34:35]
	v_lshl_add_u64 v[36:37], v[32:33], 0, v[36:37]
	global_load_ushort a10, v[36:37], off
.LBB0_425:
	s_or_b64 exec, exec, s[0:1]
	v_or_b32_e32 v36, 1, v34
	v_cmp_le_i32_e32 vcc, s30, v36
	v_cmp_gt_i32_e64 s[4:5], s31, v36
	s_and_b64 s[4:5], vcc, s[4:5]
	s_and_saveexec_b64 s[0:1], s[4:5]
	s_cbranch_execz .LBB0_427
	v_ashrrev_i32_e32 v37, 31, v36
	v_lshlrev_b64 v[36:37], 10, v[36:37]
	v_lshl_add_u64 v[36:37], v[32:33], 0, v[36:37]
	global_load_short_d16_hi a11, v[36:37], off
.LBB0_427:
	s_or_b64 exec, exec, s[0:1]
	v_or_b32_e32 v36, 2, v34
	v_cmp_le_i32_e32 vcc, s30, v36
	v_cmp_gt_i32_e64 s[4:5], s31, v36
	s_and_b64 s[4:5], vcc, s[4:5]
	v_accvgpr_write_b32 a13, 0
	v_accvgpr_write_b32 a12, 0
	s_and_saveexec_b64 s[0:1], s[4:5]
	s_cbranch_execz .LBB0_429
	v_ashrrev_i32_e32 v37, 31, v36
	v_lshlrev_b64 v[36:37], 10, v[36:37]
	v_lshl_add_u64 v[36:37], v[32:33], 0, v[36:37]
	global_load_ushort a12, v[36:37], off
.LBB0_429:
	s_or_b64 exec, exec, s[0:1]
	v_or_b32_e32 v36, 3, v34
	v_cmp_le_i32_e32 vcc, s30, v36
	v_cmp_gt_i32_e64 s[4:5], s31, v36
	s_and_b64 s[4:5], vcc, s[4:5]
	s_and_saveexec_b64 s[0:1], s[4:5]
	s_cbranch_execz .LBB0_431
	v_ashrrev_i32_e32 v37, 31, v36
	v_lshlrev_b64 v[36:37], 10, v[36:37]
	v_lshl_add_u64 v[36:37], v[32:33], 0, v[36:37]
	global_load_short_d16_hi a13, v[36:37], off
.LBB0_431:
	s_or_b64 exec, exec, s[0:1]
	v_or_b32_e32 v36, 4, v34
	v_cmp_le_i32_e32 vcc, s30, v36
	v_cmp_gt_i32_e64 s[4:5], s31, v36
	s_and_b64 s[4:5], vcc, s[4:5]
	v_accvgpr_write_b32 a15, 0
	v_accvgpr_write_b32 a14, 0
	s_and_saveexec_b64 s[0:1], s[4:5]
	s_cbranch_execz .LBB0_433
	v_ashrrev_i32_e32 v37, 31, v36
	v_lshlrev_b64 v[36:37], 10, v[36:37]
	v_lshl_add_u64 v[36:37], v[32:33], 0, v[36:37]
	global_load_ushort a14, v[36:37], off
.LBB0_433:
	s_or_b64 exec, exec, s[0:1]
	v_or_b32_e32 v36, 5, v34
	v_cmp_le_i32_e32 vcc, s30, v36
	v_cmp_gt_i32_e64 s[4:5], s31, v36
	s_and_b64 s[4:5], vcc, s[4:5]
	s_and_saveexec_b64 s[0:1], s[4:5]
	s_cbranch_execz .LBB0_435
	v_ashrrev_i32_e32 v37, 31, v36
	v_lshlrev_b64 v[36:37], 10, v[36:37]
	v_lshl_add_u64 v[36:37], v[32:33], 0, v[36:37]
	global_load_short_d16_hi a15, v[36:37], off
.LBB0_435:
	s_or_b64 exec, exec, s[0:1]
	v_or_b32_e32 v36, 6, v34
	v_cmp_le_i32_e32 vcc, s30, v36
	v_cmp_gt_i32_e64 s[4:5], s31, v36
	s_and_b64 s[4:5], vcc, s[4:5]
	v_accvgpr_write_b32 a17, 0
	v_accvgpr_write_b32 a16, 0
	s_and_saveexec_b64 s[0:1], s[4:5]
	s_cbranch_execz .LBB0_437
	v_ashrrev_i32_e32 v37, 31, v36
	v_lshlrev_b64 v[36:37], 10, v[36:37]
	v_lshl_add_u64 v[36:37], v[32:33], 0, v[36:37]
	global_load_ushort a16, v[36:37], off
.LBB0_437:
	s_or_b64 exec, exec, s[0:1]
	v_or_b32_e32 v36, 7, v34
	v_cmp_le_i32_e32 vcc, s30, v36
	v_cmp_gt_i32_e64 s[4:5], s31, v36
	s_and_b64 s[4:5], vcc, s[4:5]
	s_and_saveexec_b64 s[0:1], s[4:5]
	s_cbranch_execz .LBB0_439
	v_ashrrev_i32_e32 v37, 31, v36
	v_lshlrev_b64 v[36:37], 10, v[36:37]
	v_lshl_add_u64 v[36:37], v[32:33], 0, v[36:37]
	global_load_short_d16_hi a17, v[36:37], off
.LBB0_439:
	s_or_b64 exec, exec, s[0:1]
	v_add_u32_e32 v34, 8, v34
	v_cmp_le_i32_e32 vcc, s30, v34
	v_cmp_gt_i32_e64 s[4:5], s31, v34
	s_and_b64 s[4:5], vcc, s[4:5]
	v_accvgpr_write_b32 a18, 0
	s_and_saveexec_b64 s[0:1], s[4:5]
	s_cbranch_execz .LBB0_441
	v_ashrrev_i32_e32 v35, 31, v34
	v_lshlrev_b64 v[34:35], 10, v[34:35]
	v_lshl_add_u64 v[32:33], v[32:33], 0, v[34:35]
	global_load_ushort a18, v[32:33], off
.LBB0_441:
	s_or_b64 exec, exec, s[0:1]
	v_mov_b32_e32 v32, v38
